# XCD-local grid barriers at P5|P7 and P7|P8 (tiles of these phases are produced and consumed on one XCD), guarded by a run-time placement check with fall-back to the full barrier
# speedup vs baseline: 1.0261x; 1.0020x over previous
; #define LAS __attribute__((address_space(3)))
; __device__ __forceinline__ unsigned xb_add(unsigned* p, unsigned v) { return __hip_atomic_fetch_add(p, v, __ATOMIC_RELAXED, __HIP_MEMORY_SCOPE_AGENT); }
; __device__ __forceinline__ unsigned xb_xcc_id() { return (unsigned)__builtin_amdgcn_s_getreg((3 << 11) | 20) & 0xFu; }
; __device__ __forceinline__ XcdBarrier xcd_barrier_post(unsigned* bar, volatile LAS unsigned* st) {
;     XcdBarrier b; b.bar = bar; b.x = xb_xcc_id(); b.st = st;
;     if (threadIdx.x == 0) (void)xb_add(&bar[XB_XCNT(b.x)], 1u);
;     return b;
; __global__ void __launch_bounds__(NTHR, 2) fwd_megakernel(Args a) {
;     ...
;     const int tid = threadIdx.x, lane = tid & 63, wave = __builtin_amdgcn_readfirstlane(tid >> 6);
;     const int G = gridDim.x, blk = blockIdx.x;
;     const int vcu = (G % 8 == 0) ? (blk % 8) * (G / 8) + blk / 8 : blk;
;     const int gw = vcu * 8 + wave, NGW = G * 8;
;     const float *x = a.in[0], *cvec = a.in[1], *w_ada = a.in[2], *b_ada = a.in[3], *g1 = a.in[4], *w_in = a.in[5], *lbl = a.in[6], *ogain = a.in[7], *qg = a.in[8], *kg = a.in[9], *sinks = a.in[10],
;                 *w_a = a.in[11], *w_b = a.in[12], *w_o = a.in[13], *g2 = a.in[14], *w1 = a.in[15], *w2 = a.in[16];
;     unsigned char* ws = a.ws;
;     float* mod = (float*)(ws + WS_MOD);
;     bf16_t *WinT = (bf16_t*)(ws + WS_WIN), *WabT = (bf16_t*)(ws + WS_WAB), *WoT = (bf16_t*)(ws + WS_WO), *W1T = (bf16_t*)(ws + WS_W1), *W2T = (bf16_t*)(ws + WS_W2);
;     bf16_t *H = (bf16_t*)(ws + WS_H), *P = (bf16_t*)(ws + WS_P), *U = (bf16_t*)(ws + WS_P);
;     float* out = a.out;
;     float* LOGF = out;
;     bf16_t* OAB = (bf16_t*)(out + (size_t)M * 1024);
;     float* SSEG = (float*)(ws + WS_SSEG); float* DSEG = (float*)(ws + WS_DSEG);
;     bf16_t* H2 = (bf16_t*)(ws + WS_H2); float* cb = (float*)(ws + WS_CB); float* part = (float*)(ws + WS_PART);
;     volatile LAS unsigned* MISC = (volatile LAS unsigned*)(lds + MISC_OFF);
;     if (tid < 16) MISC[tid] = 0u;
;     __syncthreads();
;     XcdBarrier bar = xcd_barrier_post((unsigned*)(ws + WS_BAR), MISC + 8);
_Z14fwd_megakernel4Args:
	s_load_dwordx8 s[56:63], s[0:1], 0x80
	s_mov_b32 s55, s2
	v_mov_b32_e32 v237, s55
	s_add_u32 s2, s0, 0x98
	s_addc_u32 s3, s1, 0
	v_and_b32_e32 v186, 0x3ff, v0
	s_waitcnt lgkmcnt(0)
	s_and_b32 s4, s62, 7
	v_readfirstlane_b32 s22, v186
	s_cmp_lg_u32 s4, 0
	v_writelane_b32 v236, s55, 0
	s_cbranch_scc1 .LBB0_2
	s_ashr_i32 s5, s55, 31
	s_lshr_b32 s5, s5, 29
	s_add_i32 s5, s55, s5
	s_and_b32 s6, s5, -8
	s_ashr_i32 s4, s62, 3
	s_sub_i32 s6, s55, s6
	s_mul_i32 s4, s4, s6
	s_ashr_i32 s5, s5, 3
	s_add_i32 s4, s4, s5
	v_writelane_b32 v236, s4, 0
.LBB0_2:
	s_load_dword s4, s[0:1], 0xa0
	v_cmp_gt_u32_e32 vcc, 16, v186
	v_lshl_add_u32 v187, v186, 2, 0
	s_waitcnt lgkmcnt(0)
	v_writelane_b32 v236, s4, 1
	s_and_saveexec_b64 s[4:5], vcc
	v_add_u32_e32 v1, 0x23fc0, v187
	v_mov_b32_e32 v2, 0
	ds_write_b32 v1, v2
	s_or_b64 exec, exec, s[4:5]
	s_add_u32 s4, s60, 0x80000
	s_addc_u32 s5, s61, 0
	v_writelane_b32 v236, s4, 2
	s_waitcnt lgkmcnt(0)
	s_barrier
	v_writelane_b32 v236, s5, 3
	s_getreg_b32 s4, hwreg(HW_REG_XCC_ID, 0, 4)
	s_and_b32 s4, s4, 15
	v_writelane_b32 v236, s4, 4
	v_cmp_eq_u32_e64 s[6:7], 0, v186
	s_mov_b64 s[4:5], exec
	s_nop 0
	v_writelane_b32 v236, s6, 5
	s_nop 1
	v_writelane_b32 v236, s7, 6
	s_and_b64 s[6:7], s[4:5], s[6:7]
	s_mov_b64 exec, s[6:7]
	s_cbranch_execz .LBB0_7
	s_mov_b64 s[6:7], exec
	v_mbcnt_lo_u32_b32 v1, s6, 0
	v_mbcnt_hi_u32_b32 v1, s7, v1
	v_cmp_eq_u32_e32 vcc, 0, v1
	s_and_b64 s[8:9], exec, vcc
	s_mov_b64 exec, s[8:9]
	s_cbranch_execz .LBB0_7
	v_readlane_b32 s8, v236, 4
	s_bcnt1_i32_b64 s6, s[6:7]
	s_lshl_b32 s8, s8, 8
	v_mov_b32_e32 v2, s6
	v_readlane_b32 s6, v236, 2
	v_mov_b32_e32 v1, s8
	v_readlane_b32 s7, v236, 3
	s_nop 4
	global_atomic_add v1, v2, s[6:7] offset:1024
	s_lshr_b32 s9, s55, 5
	s_lshl_b32 s9, s9, 8
	s_and_b32 s10, s55, 31
	s_lshl_b32 s10, s10, 2
	s_add_i32 s9, s9, s10
	s_add_i32 s9, s9, 0x404
	v_mov_b32_e32 v3, s9
	v_readlane_b32 s10, v236, 4
	s_nop 3
	s_add_i32 s10, s10, 1
	v_mov_b32_e32 v4, s10
	global_store_dword v3, v4, s[6:7] sc0 sc1

; #define LAS __attribute__((address_space(3)))
; #define GRID_SYNC() xcd_barrier(bar)
; template <bool FULL>
; __device__ __forceinline__ void hgrn_seg(int b, int h, int sg, const bf16_t* P, const float* LOGF, const float* __restrict__ ogain, bf16_t* OA, float* SSEG, float* DSEG, LAS unsigned char* lds, int tid) {
;     const int lane = tid & 63, wid = __builtin_amdgcn_readfirstlane(tid >> 6), fr = lane & 15, fq = lane >> 4;
;     LAS bf16_t* Qd = (LAS bf16_t*)lds;
;     LAS bf16_t* Kd = Qd + 64 * 136;
;     LAS bf16_t* Qb = Kd + 64 * 136;
;     LAS bf16_t* KlT = Qb + 64 * 136;
;     LAS bf16_t* VT = KlT + 128 * 72;
;     LAS bf16_t* Pm = VT + 128 * 72;
;     LAS bf16_t* ST = Pm + 64 * 72;
;     LAS float* segtot = (LAS float*)(ST + 128 * 136);
;     LAS float* dec = segtot + 1024;
;     LAS float* rsq = dec + 128;
;     const int unit = (b * 8 + h) * 8 + sg;
;     f32x4 sacc[8];
; #pragma unroll
;     for (int kt = 0; kt < 8; ++kt) sacc[kt] = (f32x4){0.f, 0.f, 0.f, 0.f};
;     const int kp = lane, t0 = wid * 8;
;     const int tt = wid & 3, vh = wid >> 2;
; __global__ void __launch_bounds__(NTHR, 2) fwd_megakernel(Args a) {
;     ...
;     GRID_SYNC();
;     for (int u = blk; u < 256; u += G) { const int us = 256 + u;
;         hgrn_seg<true>(u >> 6, (u >> 3) & 7, u & 7, P, LOGF, ogain, OAB + (size_t)M * 1024, SSEG, DSEG, lds, tid);
.LBB0_471:
	s_or_b64 exec, exec, s[0:1]
	v_readlane_b32 s98, v236, 2
	v_readlane_b32 s99, v236, 3
	v_add_u32_e32 v239, 8, v237
	v_and_b32_e32 v239, 0xff, v239
	v_lshrrev_b32_e32 v238, 5, v239
	v_and_b32_e32 v239, 31, v239
	v_lshlrev_b32_e32 v238, 8, v238
	v_lshl_add_u32 v238, v239, 2, v238
	v_add_u32_e32 v238, 0x404, v238
	global_load_dword v238, v238, s[98:99] sc0 sc1
	v_readlane_b32 s0, v235, 1
	v_readlane_b32 s1, v235, 2
	s_and_b64 vcc, exec, s[0:1]
	s_waitcnt lgkmcnt(0)
	s_barrier
	s_cbranch_vccnz .LBB0_501
	v_readlane_b32 s4, v236, 7
	v_readlane_b32 s5, v236, 8
	v_readlane_b32 s6, v236, 9
	v_readlane_b32 s7, v236, 10
	v_readlane_b32 s8, v236, 11
	v_readlane_b32 s9, v236, 12
	v_readlane_b32 s10, v236, 13
	v_readlane_b32 s11, v236, 14
	v_readlane_b32 s4, v236, 56
	v_readlane_b32 s5, v236, 57
	s_movk_i32 s3, 0x1ff
	v_cmp_lt_u32_e64 s[4:5], s3, v186
	v_lshrrev_b32_e32 v0, 4, v160
	s_add_i32 s2, 0, 0x18000
	v_mul_u32_u24_e32 v3, 0x90, v160
	v_writelane_b32 v235, s4, 9
	v_lshlrev_b32_e32 v93, 2, v0
	v_lshl_add_u32 v154, v0, 3, s2
	v_and_b32_e32 v0, 48, v160
	v_mov_b32_e32 v1, 0
	v_readlane_b32 s12, v236, 15
	v_readlane_b32 s13, v236, 16
	v_readlane_b32 s14, v236, 17
	v_readlane_b32 s15, v236, 18
	v_readlane_b32 s16, v236, 19
	v_readlane_b32 s17, v236, 20
	v_readlane_b32 s18, v236, 21
	v_readlane_b32 s19, v236, 22
	v_writelane_b32 v235, s5, 10
	v_lshlrev_b32_e32 v3, 1, v3
	s_add_i32 s4, 0, 0x11400
	v_lshl_add_u64 v[86:87], s[18:19], 0, v[0:1]
	v_and_b32_e32 v2, 56, v188
	v_readlane_b32 s12, v236, 23
	v_add_u32_e32 v167, s4, v3
	v_add_u32_e32 v168, s4, v0
	s_add_i32 s4, 0, 0x15c00
	v_readlane_b32 s8, v236, 60
	v_readlane_b32 s9, v236, 61
	v_add_u32_e32 v157, 0, v0
	v_lshlrev_b32_e32 v4, 2, v2
	v_mov_b32_e32 v5, v1
	v_readlane_b32 s13, v236, 24
	v_readlane_b32 s14, v236, 25
	v_readlane_b32 s15, v236, 26
	v_add_u32_e32 v169, s4, v0
	v_add_u32_e32 v170, s2, v0
	v_lshlrev_b32_e32 v0, 2, v160
	v_lshl_add_u64 v[108:109], s[14:15], 0, v[4:5]
	v_lshl_add_u64 v[110:111], s[12:13], 0, v[4:5]
	v_mul_u32_u24_e32 v4, 0x150, v91
	s_add_i32 s3, 0, 0x16800
	v_and_b32_e32 v5, 24, v188
	v_lshl_add_u64 v[112:113], s[8:9], 0, v[0:1]
	v_lshrrev_b32_e32 v0, 1, v90
	v_readlane_b32 s6, v236, 58
	v_readlane_b32 s7, v236, 59
	v_add_u32_e32 v165, 0, v5
	v_add3_u32 v171, s3, v4, v94
	v_lshl_add_u64 v[4:5], s[8:9], 0, v[0:1]
	s_mov_b64 s[2:3], 0xb801040
	v_mov_b32_e32 v95, v1
	v_lshl_add_u64 v[114:115], v[4:5], 0, s[2:3]
	v_lshl_add_u64 v[4:5], s[6:7], 0, v[94:95]
	s_mov_b64 s[2:3], 0x4000040
	v_writelane_b32 v235, s4, 5
	v_lshl_add_u64 v[118:119], v[4:5], 0, s[2:3]
	s_add_i32 s2, 0, 0x21a00
	v_lshlrev_b32_e32 v98, 3, v160
	v_mov_b32_e32 v99, v1
	s_add_i32 s0, 0, 0x20800
	s_movk_i32 s59, 0x90
	v_lshl_add_u32 v6, v2, 1, 0
	v_mul_u32_u24_e32 v7, 0x48, v88
	v_lshlrev_b32_e32 v0, 4, v97
	v_writelane_b32 v235, s2, 1
	v_lshl_add_u64 v[100:101], s[6:7], 0, v[98:99]
	v_add_u32_e32 v99, s0, v98
	s_add_i32 s0, 0, 0x21800
	v_mad_u32_u24 v158, v91, s59, v157
	v_lshl_add_u32 v162, v7, 1, v6
	v_mul_u32_u24_e32 v7, 0x90, v88
	v_lshl_add_u64 v[116:117], s[8:9], 0, v[0:1]
	v_mbcnt_lo_u32_b32 v0, -1, 0
	v_readlane_b32 s92, v235, 0
	s_mov_b32 s97, 0
	v_lshl_add_u32 v155, v160, 2, 0
	v_add_u32_e32 v156, s0, v98
	v_cmp_gt_u32_e64 s[0:1], 16, v160
	v_add_u32_e32 v159, 0xcc00, v158
	v_mov_b32_e32 v89, v1
	v_add_u32_e32 v102, 64, v88
	v_mov_b32_e32 v103, v1
	v_or_b32_e32 v104, 0x80, v88
	v_mov_b32_e32 v105, v1
	v_add_u32_e32 v106, 0xc0, v88
	v_mov_b32_e32 v107, v1
	v_add_u32_e32 v163, 0xd800, v162
	v_or_b32_e32 v164, v94, v185
	v_add_u32_e32 v166, 0, v3
	s_movk_i32 s58, 0x4400
	v_lshlrev_b32_e32 v96, 1, v96
	s_mov_b32 s33, 0xffff0000
	s_mov_b32 s90, 0xffff
	v_mov_b32_e32 v95, 0x358637bd
	s_mov_b32 s91, 0xf800000
	v_mov_b32_e32 v172, 0x260
	v_lshlrev_b32_e32 v120, 1, v2
	s_mov_b32 s93, 0x3e000000
	v_add_u32_e32 v173, v6, v7
	v_mov_b32_e32 v174, 0x4400
	v_mbcnt_hi_u32_b32 v175, -1, v0
	v_mov_b32_e32 v176, 0xffffff80
	v_mov_b32_e32 v177, 0xff800000
	s_mov_b32 s94, s92
	s_mov_b32 s95, s92
	v_readlane_b32 s10, v236, 62
	v_readlane_b32 s11, v236, 63
	v_readlane_b32 s16, v236, 27
	v_readlane_b32 s17, v236, 28
	v_readlane_b32 s18, v236, 29
	v_readlane_b32 s19, v236, 30
	v_readlane_b32 s20, v236, 31
	v_readlane_b32 s21, v236, 32
	v_readlane_b32 s22, v236, 33
	v_readlane_b32 s23, v236, 34
	v_readlane_b32 s24, v236, 35
	v_readlane_b32 s25, v236, 36
	v_readlane_b32 s26, v236, 37
	v_readlane_b32 s27, v236, 38
	s_branch .LBB0_474

; #define GRID_SYNC() xcd_barrier(bar)
; __device__ __forceinline__ void xcd_barrier(const XcdBarrier& b) {
;     asm volatile("s_waitcnt vmcnt(0)" ::: "memory");
;     __syncthreads();
; __global__ void __launch_bounds__(NTHR, 2) fwd_megakernel(Args a) {
;     ...
;     GRID_SYNC();
;     {
;         pg8::Gemm g{OAB, WabT, 2 * M, 2 * DM, 1024}; pg8::PairOrder S; S.base.init(M, DM, G, blk);
.LBB0_553:
	s_or_b64 exec, exec, s[0:1]
	s_getreg_b32 s98, hwreg(HW_REG_XCC_ID, 0, 4)
	s_add_i32 s98, s98, 1
	s_waitcnt vmcnt(0)
	v_cmp_ne_u32_e64 s[100:101], s98, v238
	s_cmp_eq_u64 s[100:101], 0
	s_cbranch_scc1 .Lplace_ok
	v_readlane_b32 s98, v236, 2
	v_readlane_b32 s99, v236, 3
	v_mov_b32_e32 v239, 0x100
	v_mov_b32_e32 v238, 1
	s_nop 4
	global_atomic_add v239, v238, s[98:99]
.Lplace_ok:
	v_mov_b32_e32 v8, v186
	s_cmpk_lt_i32 s62, 0x200
	s_waitcnt lgkmcnt(0)
	s_barrier
	s_cselect_b64 s[2:3], -1, 0
	s_cmpk_gt_i32 s62, 0x1ff
	v_readfirstlane_b32 s4, v8
	s_cbranch_scc1 .LBB0_559
	s_ashr_i32 s0, s62, 31
	s_lshr_b32 s0, s0, 29
	s_add_i32 s5, s62, s0
	s_and_b32 s0, s5, -8
	s_sub_i32 s6, s62, s0
	s_cmp_gt_i32 s6, -1
	s_cbranch_scc0 .LBB0_556
	s_lshl_b32 s7, s6, 6
	s_cbranch_execz .LBB0_557
	s_branch .LBB0_558

;     __device__ __forceinline__ bool next(int i, Unit& u) const { if (!base.next(i >> 1, u)) return false; if (i & 1) { u.pm += 64; u.pn += 8; } return true; }
; #define GRID_SYNC() xcd_barrier(bar)
;     __device__ bool next(int i, Unit& u) const {
;         const long L = (long)i * G + c; if (L >= nwg) return false;
;         int wgid = (int)L; { const int q = nwg / NXCD, r = nwg % NXCD, xcd = wgid % NXCD, off = wgid / NXCD; wgid = (xcd < r ? xcd * (q + 1) : r * (q + 1) + (xcd - r) * q) + off; }
; __global__ void __launch_bounds__(NTHR, 2) fwd_megakernel(Args a) {
;     ...
;     GRID_SYNC();
;     if (G == 256) {
;     {
;         pg8::Gemm g{H, WoT, M, DM, DM}; pg8::StaticOrderW<4> S; S.init(M, DM, G, blk);
;         pg8::EpiRes3 E{x, out, mod, g2, H2, part};
;         pg8::gemm_phase<pg8::EpiRes3, pg8::StaticOrderW<4>, true, true>(lds, g, S, E);
.LBB0_663:
	s_or_b64 exec, exec, s[2:3]
	v_readlane_b32 s98, v236, 2
	v_readlane_b32 s99, v236, 3
	v_mov_b32_e32 v238, 0x100
	s_nop 4
	global_load_dword v238, v238, s[98:99] sc0 sc1
	v_readlane_b32 s4, v235, 7
	v_readlane_b32 s5, v235, 8
	s_mov_b64 s[2:3], -1
	s_and_b64 vcc, exec, s[4:5]
	s_waitcnt lgkmcnt(0)
	s_barrier
	s_cbranch_vccz .LBB0_874
	v_mov_b32_e32 v8, v186
	s_and_b64 vcc, exec, s[0:1]
	v_readfirstlane_b32 s5, v8
	s_cbranch_vccnz .LBB0_688
	s_ashr_i32 s33, s62, 31
	s_lshr_b32 s2, s33, 29
	s_add_i32 s6, s62, s2
	s_and_b32 s2, s6, -8
	s_sub_i32 s7, s62, s2
	s_cmp_gt_i32 s7, -1
	s_cbranch_scc0 .LBB0_667
	s_lshl_b32 s4, s7, 6
	s_cbranch_execz .LBB0_668
	s_branch .LBB0_669

; __device__ __forceinline__ unsigned xb_add(unsigned* p, unsigned v) { return __hip_atomic_fetch_add(p, v, __ATOMIC_RELAXED, __HIP_MEMORY_SCOPE_AGENT); }
; __device__ __forceinline__ void xcd_barrier(const XcdBarrier& b) {
;     ...
;         const unsigned old = xb_add(&bar[XB_XSUB(b.x)], 1u);
;         const unsigned gen = old / nloc;
;         if (old + 1u == (gen + 1u) * nloc) {
;             __builtin_amdgcn_fence(__ATOMIC_RELEASE, "agent");
;             asm volatile("s_waitcnt vmcnt(0)" ::: "memory");
;             const unsigned og = xb_add(&bar[XB_TOP], 1u);
;             const unsigned tg = og / nx;
;             if (og + 1u == (tg + 1u) * nx) xb_add(&bar[XB_TOPGEN], 1u);
.LBB0_949:
	s_andn2_saveexec_b64 s[6:7], s[6:7]
	s_cbranch_execz .LBB0_969
	s_mov_b64 s[6:7], exec
	v_readfirstlane_b32 s98, v238
	s_cmp_eq_u32 s98, 0
	s_cbranch_scc0 .Lfullbar_57
	buffer_inv sc1
	s_branch .LBB0_966
.Lfullbar_57:
	buffer_wbl2 sc1
	buffer_inv sc1
	s_waitcnt lgkmcnt(0)
	s_waitcnt vmcnt(0)
	v_mbcnt_lo_u32_b32 v1, s6, 0
	v_mbcnt_hi_u32_b32 v1, s7, v1
	v_cmp_eq_u32_e32 vcc, 0, v1
	s_and_saveexec_b64 s[10:11], vcc
	s_cbranch_execz .LBB0_952
	s_bcnt1_i32_b64 s6, s[6:7]
	v_mov_b32_e32 v2, 0x83000
	v_mov_b32_e32 v3, s6
	global_atomic_add v2, v2, v3, s[68:69] offset:1024 sc0

; __device__ __forceinline__ unsigned xb_add(unsigned* p, unsigned v) { return __hip_atomic_fetch_add(p, v, __ATOMIC_RELAXED, __HIP_MEMORY_SCOPE_AGENT); }
; __device__ __forceinline__ void xcd_barrier(const XcdBarrier& b) {
;     ...
;         if (old + 1u == (gen + 1u) * nloc) {
;             __builtin_amdgcn_fence(__ATOMIC_RELEASE, "agent");
;             asm volatile("s_waitcnt vmcnt(0)" ::: "memory");
;             const unsigned og = xb_add(&bar[XB_TOP], 1u);
;             const unsigned tg = og / nx;
;             if (og + 1u == (tg + 1u) * nx) xb_add(&bar[XB_TOPGEN], 1u);
.Lfullbar_78:
	buffer_wbl2 sc1
	buffer_inv sc1
	s_waitcnt lgkmcnt(0)
	s_waitcnt vmcnt(0)
	v_mbcnt_lo_u32_b32 v1, s6, 0
	v_mbcnt_hi_u32_b32 v1, s7, v1
	v_cmp_eq_u32_e32 vcc, 0, v1
	s_and_saveexec_b64 s[8:9], vcc
	s_cbranch_execz .LBB0_1036
	s_bcnt1_i32_b64 s6, s[6:7]
	v_mov_b32_e32 v2, 0x83000
	v_mov_b32_e32 v3, s6
	global_atomic_add v2, v2, v3, s[68:69] offset:1024 sc0

; __global__ void __launch_bounds__(NTHR, 2) fwd_megakernel(Args a) {
	.amdhsa_kernel _Z14fwd_megakernel4Args
		.amdhsa_group_segment_fixed_size 0
		.amdhsa_private_segment_fixed_size 0
		.amdhsa_kernarg_size 408
		.amdhsa_user_sgpr_count 2
		.amdhsa_user_sgpr_dispatch_ptr 0
		.amdhsa_user_sgpr_queue_ptr 0
		.amdhsa_user_sgpr_kernarg_segment_ptr 1
		.amdhsa_user_sgpr_dispatch_id 0
		.amdhsa_user_sgpr_kernarg_preload_length 0
		.amdhsa_user_sgpr_kernarg_preload_offset 0
		.amdhsa_user_sgpr_private_segment_size 0
		.amdhsa_uses_dynamic_stack 0
		.amdhsa_enable_private_segment 0
		.amdhsa_system_sgpr_workgroup_id_x 1
		.amdhsa_system_sgpr_workgroup_id_y 0
		.amdhsa_system_sgpr_workgroup_id_z 0
		.amdhsa_system_sgpr_workgroup_info 0
		.amdhsa_system_vgpr_workitem_id 2
		.amdhsa_next_free_vgpr 240
		.amdhsa_next_free_sgpr 102
		.amdhsa_accum_offset 240
		.amdhsa_reserve_vcc 1
		.amdhsa_float_round_mode_32 0
		.amdhsa_float_round_mode_16_64 0
		.amdhsa_float_denorm_mode_32 3
		.amdhsa_float_denorm_mode_16_64 3
		.amdhsa_dx10_clamp 1
		.amdhsa_ieee_mode 1
		.amdhsa_fp16_overflow 0
		.amdhsa_tg_split 0
		.amdhsa_exception_fp_ieee_invalid_op 0
		.amdhsa_exception_fp_denorm_src 0
		.amdhsa_exception_fp_ieee_div_zero 0
		.amdhsa_exception_fp_ieee_overflow 0
		.amdhsa_exception_fp_ieee_underflow 0
		.amdhsa_exception_fp_ieee_inexact 0
		.amdhsa_exception_int_div_zero 0
	.end_amdhsa_kernel

; __global__ void __launch_bounds__(NTHR, 2) fwd_megakernel(Args a) {
amdhsa.kernels:
  - .agpr_count:     0
    .args:
      - .offset:         0
        .size:           152
        .value_kind:     by_value
      - .offset:         152
        .size:           4
        .value_kind:     hidden_block_count_x
      - .offset:         156
        .size:           4
        .value_kind:     hidden_block_count_y
      - .offset:         160
        .size:           4
        .value_kind:     hidden_block_count_z
      - .offset:         164
        .size:           2
        .value_kind:     hidden_group_size_x
      - .offset:         166
        .size:           2
        .value_kind:     hidden_group_size_y
      - .offset:         168
        .size:           2
        .value_kind:     hidden_group_size_z
      - .offset:         170
        .size:           2
        .value_kind:     hidden_remainder_x
      - .offset:         172
        .size:           2
        .value_kind:     hidden_remainder_y
      - .offset:         174
        .size:           2
        .value_kind:     hidden_remainder_z
      - .offset:         192
        .size:           8
        .value_kind:     hidden_global_offset_x
      - .offset:         200
        .size:           8
        .value_kind:     hidden_global_offset_y
      - .offset:         208
        .size:           8
        .value_kind:     hidden_global_offset_z
      - .offset:         216
        .size:           2
        .value_kind:     hidden_grid_dims
      - .offset:         240
        .size:           8
        .value_kind:     hidden_multigrid_sync_arg
      - .offset:         272
        .size:           4
        .value_kind:     hidden_dynamic_lds_size
    .group_segment_fixed_size: 0
    .kernarg_segment_align: 8
    .kernarg_segment_size: 408
    .language:       OpenCL C
    .language_version:
      - 2
      - 0
    .max_flat_workgroup_size: 512
    .name:           _Z14fwd_megakernel4Args
    .private_segment_fixed_size: 0
    .sgpr_count:     108
    .sgpr_spill_count: 83
    .symbol:         _Z14fwd_megakernel4Args.kd
    .uniform_work_group_size: 1
    .uses_dynamic_stack: false
    .vgpr_count:     240
    .vgpr_spill_count: 0
    .wavefront_size: 64
